# v90 + phase 0 row sum of squares via DPP / permlane-swap butterflies (bit-identical pairing) instead of six ds_bpermute round trips per row
# speedup vs baseline: 1.0100x; 1.0100x over previous
.LBB0_25:
	v_add_u32_e32 v2, 0xffffc000, v0
	v_lshlrev_b64 v[24:25], 12, v[2:3]
	v_lshl_add_u64 v[24:25], s[10:11], 0, v[24:25]
	v_cmp_gt_i32_e64 s[6:7], s5, v0
	v_mov_b32_e32 v11, v3
	s_nop 0
	v_cndmask_b32_e64 v25, v25, v7, s[6:7]
	v_cndmask_b32_e64 v24, v24, v6, s[6:7]
	v_lshl_add_u64 v[36:37], v[24:25], 0, v[10:11]
	global_load_dwordx4 v[24:27], v[36:37], off
	global_load_dwordx4 v[28:31], v[36:37], off offset:1024
	global_load_dwordx4 v[32:35], v[36:37], off offset:2048
	global_load_dwordx4 v[36:39], v[36:37], off offset:3072
	v_cmp_lt_i32_e64 s[6:7], v16, v17
	s_waitcnt vmcnt(3)
	v_cvt_pk_bf16_f32 v40, v24, v25
	v_cvt_pk_bf16_f32 v41, v26, v27
	global_store_dwordx2 v[12:13], v[40:41], off
	v_mul_f32_e32 v11, v25, v25
	v_fmac_f32_e32 v11, v24, v24
	v_fmac_f32_e32 v11, v26, v26
	v_fmac_f32_e32 v11, v27, v27
	v_cndmask_b32_e64 v2, v15, v16, s[6:7]
	v_lshlrev_b32_e32 v2, 2, v2
	v_cmp_lt_i32_e64 s[6:7], v18, v17
	s_waitcnt vmcnt(3)
	v_cvt_pk_bf16_f32 v42, v28, v29
	v_cvt_pk_bf16_f32 v43, v30, v31
	global_store_dwordx2 v[12:13], v[42:43], off offset:512
	s_waitcnt lgkmcnt(0)
	v_mul_f32_e32 v23, v29, v29
	v_fmac_f32_e32 v23, v28, v28
	v_fmac_f32_e32 v23, v30, v30
	v_fmac_f32_e32 v23, v31, v31
	v_add_f32_e32 v11, v11, v23
	s_waitcnt vmcnt(3)
	v_cvt_pk_bf16_f32 v44, v32, v33
	v_cvt_pk_bf16_f32 v45, v34, v35
	global_store_dwordx2 v[12:13], v[44:45], off offset:1024
	v_mul_f32_e32 v23, v33, v33
	v_fmac_f32_e32 v23, v32, v32
	v_fmac_f32_e32 v23, v34, v34
	v_fmac_f32_e32 v23, v35, v35
	v_add_f32_e32 v11, v11, v23
	s_waitcnt vmcnt(3)
	v_mul_f32_e32 v23, v37, v37
	v_fmac_f32_e32 v23, v36, v36
	v_fmac_f32_e32 v23, v38, v38
	v_fmac_f32_e32 v23, v39, v39
	v_add_f32_e32 v11, v11, v23
	v_cvt_pk_bf16_f32 v24, v36, v37
	v_cvt_pk_bf16_f32 v25, v38, v39
	global_store_dwordx2 v[12:13], v[24:25], off offset:1536
	s_mov_b64 s[6:7], s[24:25]
	s_nop 1
	v_add_f32_dpp v11, v11, v11 quad_perm:[1,0,3,2] row_mask:0xf bank_mask:0xf bound_ctrl:1
	s_nop 1
	v_add_f32_dpp v11, v11, v11 quad_perm:[2,3,0,1] row_mask:0xf bank_mask:0xf bound_ctrl:1
	s_nop 1
	v_add_f32_dpp v11, v11, v11 row_half_mirror row_mask:0xf bank_mask:0xf bound_ctrl:1
	s_nop 1
	v_add_f32_dpp v11, v11, v11 row_mirror row_mask:0xf bank_mask:0xf bound_ctrl:1
	v_mov_b32_e32 v23, v11
	s_nop 1
	v_permlane16_swap_b32_e32 v11, v23
	s_nop 0
	v_add_f32_e32 v11, v11, v23
	v_mov_b32_e32 v23, v11
	s_nop 1
	v_permlane32_swap_b32_e32 v11, v23
	s_nop 0
	v_add_f32_e32 v11, v11, v23
	v_mov_b32_e32 v23, 0
	s_and_saveexec_b64 s[28:29], vcc
	s_cbranch_execz .LBB0_27
	s_waitcnt lgkmcnt(0)
	v_add_f32_e32 v2, v11, v23
	v_fmamk_f32 v2, v2, 0x3a800000, v1
	v_mul_f32_e32 v11, 0x4b800000, v2
	v_cmp_gt_f32_e64 s[6:7], s17, v2
	s_nop 1
	v_cndmask_b32_e64 v2, v2, v11, s[6:7]
	v_rsq_f32_e32 v2, v2
	s_nop 0
	v_mul_f32_e32 v11, 0x45800000, v2
	v_cndmask_b32_e64 v2, v2, v11, s[6:7]
	s_or_b64 s[6:7], s[24:25], exec
